# P8 tile order remapped: per XCD round 4 row panels x 8 weight column tiles instead of 2 x 16 (less fabric traffic per K-step)
# baseline (speedup 1.0000x reference)
.LBB0_1220:
	s_and_b32 s18, s82, 7
	s_lshr_b32 s19, s82, 3
	s_lshl_b32 s18, s18, 3
	s_and_b32 s7, s19, 3
	s_add_i32 s18, s18, s7
	s_lshr_b32 s19, s19, 2
	v_writelane_b32 v253, s18, 9
	v_writelane_b32 v253, s19, 17
	v_mov_b32_e32 v1, v0
	s_mov_b64 s[6:7], s[72:73]
	s_waitcnt vmcnt(1)
	v_mov_b32_e32 v12, v0
	s_and_b64 vcc, exec, s[38:39]
	v_readfirstlane_b32 s18, v12
	s_cbranch_vccnz .LBB0_1294
	v_lshlrev_b32_e32 v1, 4, v12
	v_add_u32_e32 v2, 0x2000, v1
	v_ashrrev_i32_e32 v4, 31, v2
	v_lshrrev_b32_e32 v4, 22, v4
	v_add_u32_e32 v4, v2, v4
	v_ashrrev_i32_e32 v13, 10, v4
	v_mul_i32_i24_e32 v4, 0x400, v13
	v_sub_u32_e32 v2, v2, v4
	v_lshrrev_b32_e32 v4, 4, v2
	v_bitop3_b32 v2, v4, v2, 32 bitop3:0x6c
	v_ashrrev_i32_e32 v4, 31, v2
	v_lshrrev_b32_e32 v4, 26, v4
	v_add_u32_e32 v4, v2, v4
	s_waitcnt vmcnt(0)
	v_ashrrev_i32_e32 v14, 6, v4
	v_lshlrev_b32_e32 v6, 5, v13
	v_and_b32_e32 v4, 0xc0, v4
	v_and_b32_e32 v15, 32, v6
	v_sub_u32_e32 v2, v2, v4
	v_mov_b32_e32 v6, 1
	v_ashrrev_i16_sdwa v2, v6, sext(v2) dst_sel:DWORD dst_unused:UNUSED_PAD src0_sel:DWORD src1_sel:BYTE_0
	v_bfe_i32 v16, v2, 0, 16
	v_bfe_i32 v2, v12, 27, 1
	v_lshrrev_b32_e32 v2, 22, v2
	v_add_u32_e32 v2, v1, v2
	v_and_b32_e32 v2, 0xfffffc00, v2
	s_load_dwordx4 s[48:51], s[6:7], 0x90
	s_load_dwordx2 s[16:17], s[6:7], 0x8
	v_sub_u32_e32 v1, v1, v2
	v_lshrrev_b32_e32 v2, 4, v1
	v_ashrrev_i32_e32 v4, 31, v12
	v_bitop3_b32 v1, v2, v1, 32 bitop3:0x6c
	v_lshrrev_b32_e32 v4, 26, v4
	s_waitcnt lgkmcnt(0)
	v_lshlrev_b32_e32 v5, 3, v13
	v_ashrrev_i32_e32 v2, 31, v1
	v_add_u32_e32 v4, v12, v4
	s_add_u32 s0, s50, 0x28000000
	v_and_b32_e32 v5, 0xfffff0, v5
	v_lshrrev_b32_e32 v2, 26, v2
	v_ashrrev_i32_e32 v18, 6, v4
	s_addc_u32 s1, s51, 0
	v_add_u32_e32 v5, v14, v5
	s_movk_i32 s6, 0x2b00
	v_add_u32_e32 v2, v1, v2
	v_lshlrev_b32_e32 v4, 3, v18
	s_add_u32 s3, s50, 0x12a00000
	v_mul_lo_u32 v5, v5, s6
	v_ashrrev_i32_e32 v17, 6, v2
	v_and_b32_e32 v4, 0xfffff0, v4
	s_addc_u32 s26, s51, 0
	s_ashr_i32 s24, s18, 6
	v_or_b32_e32 v5, v5, v15
	v_add_u32_e32 v4, v17, v4
	v_and_b32_e32 v2, 0xc0, v2
	v_readlane_b32 s7, v253, 17
	s_ashr_i32 s19, s18, 8
	s_cbranch_scc0 .Lsp_p8
	s_setprio 1

.LBB0_1231:
	s_ashr_i32 s18, s24, 3
	s_add_i32 s18, s40, s18
	s_ashr_i32 s19, s18, 31
	s_lshr_b32 s19, s19, 27
	s_add_i32 s19, s18, s19
	s_ashr_i32 s24, s19, 5
	s_lshl_b32 s24, s24, 1
	s_sub_i32 s25, 64, s24
	s_min_i32 s25, s25, 2
	s_abs_i32 s40, s25
	v_cvt_f32_u32_e32 v4, s40
	s_sub_i32 s46, 0, s40
	s_andn2_b32 s19, s19, 31
	s_sub_i32 s18, s18, s19
	v_rcp_iflag_f32_e32 v4, v4
	s_abs_i32 s19, s18
	s_xor_b32 s41, s18, s25
	s_ashr_i32 s41, s41, 31
	v_mul_f32_e32 v4, 0x4f7ffffe, v4
	v_cvt_u32_f32_e32 v4, v4
	s_nop 0
	v_readfirstlane_b32 s47, v4
	s_mul_i32 s46, s46, s47
	s_mul_hi_u32 s46, s47, s46
	s_add_i32 s47, s47, s46
	s_mul_hi_u32 s46, s19, s47
	s_mul_i32 s47, s46, s40
	s_sub_i32 s19, s19, s47
	s_add_i32 s54, s46, 1
	s_sub_i32 s47, s19, s40
	s_cmp_ge_u32 s19, s40
	s_cselect_b32 s46, s54, s46
	s_cselect_b32 s19, s47, s19
	s_add_i32 s47, s46, 1
	s_cmp_ge_u32 s19, s40
	s_cselect_b32 s19, s47, s46
	s_xor_b32 s19, s19, s41
	s_sub_i32 s54, s19, s41
	s_mul_i32 s19, s54, s25
	s_sub_i32 s18, s18, s19
	s_add_i32 s55, s24, s18
	s_and_b32 s18, s82, 7
	s_lshr_b32 s19, s82, 3
	s_lshl_b32 s55, s18, 3
	s_lshr_b32 s40, s37, 1
	s_lshl_b32 s40, s40, 2
	s_add_i32 s55, s55, s40
	s_and_b32 s40, s19, 3
	s_add_i32 s55, s55, s40
	s_and_b32 s54, s37, 1
	s_lshl_b32 s54, s54, 3
	s_lshr_b32 s40, s19, 2
	s_add_i32 s54, s54, s40
